# first-rmsnorm row loop: 16 pre-norm gain loads issued together after the x loads with counted waits; mixer B per-head sink via scalar load so the next-head Q prefetch stays in flight
# baseline (speedup 1.0000x reference)
.LBB0_691:
	v_add_co_u32_e32 v2, vcc, 0xffffd000, v98
	s_nop 1
	v_addc_co_u32_e32 v3, vcc, -1, v99, vcc
	global_load_dwordx4 v[62:65], v[2:3], off offset:-3072 nt
	global_load_dwordx4 v[58:61], v[2:3], off offset:-2048 nt
	global_load_dwordx4 v[54:57], v[2:3], off offset:-1024 nt
	global_load_dwordx4 v[50:53], v[2:3], off nt
	v_add_co_u32_e32 v2, vcc, 0xffffe000, v98
	s_waitcnt vmcnt(2)
	v_mul_f32_e32 v108, v59, v59
	v_addc_co_u32_e32 v3, vcc, -1, v99, vcc
	global_load_dwordx4 v[46:49], v[2:3], off offset:-3072 nt
	global_load_dwordx4 v[42:45], v[2:3], off offset:-2048 nt
	global_load_dwordx4 v[38:41], v[2:3], off offset:-1024 nt
	global_load_dwordx4 v[34:37], v[2:3], off nt
	v_add_co_u32_e32 v106, vcc, 0xfffff000, v98
	v_mul_f32_e32 v109, v61, v61
	s_nop 0
	v_addc_co_u32_e32 v107, vcc, -1, v99, vcc
	global_load_dwordx4 v[30:33], v[106:107], off offset:-3072 nt
	global_load_dwordx4 v[26:29], v[106:107], off offset:-2048 nt
	global_load_dwordx4 v[22:25], v[106:107], off offset:-1024 nt
	global_load_dwordx4 v[18:21], v[98:99], off offset:-4096 nt
	global_load_dwordx4 v[14:17], v[98:99], off offset:-3072 nt
	global_load_dwordx4 v[10:13], v[98:99], off offset:-2048 nt
	global_load_dwordx4 v[6:9], v[98:99], off offset:-1024 nt
	global_load_dwordx4 v[2:5], v[98:99], off nt
	global_load_dwordx4 v[128:131], v[68:69], off
	global_load_dwordx4 v[132:135], v[68:69], off offset:1024
	global_load_dwordx4 v[136:139], v[68:69], off offset:2048
	global_load_dwordx4 v[140:143], v[68:69], off offset:3072
	global_load_dwordx4 v[144:147], v[70:71], off
	global_load_dwordx4 v[148:151], v[72:73], off
	global_load_dwordx4 v[152:155], v[74:75], off
	global_load_dwordx4 v[156:159], v[76:77], off
	global_load_dwordx4 v[160:163], v[78:79], off
	global_load_dwordx4 v[164:167], v[80:81], off
	global_load_dwordx4 v[168:171], v[82:83], off
	global_load_dwordx4 v[172:175], v[84:85], off
	global_load_dwordx4 v[176:179], v[86:87], off
	global_load_dwordx4 v[180:183], v[88:89], off
	global_load_dwordx4 v[184:187], v[90:91], off
	global_load_dwordx4 v[188:191], v[92:93], off
	v_mul_f32_e32 v106, v63, v63
	v_mul_f32_e32 v107, v65, v65
	s_waitcnt vmcnt(29)
	v_mul_f32_e32 v110, v55, v55
	v_mul_f32_e32 v111, v57, v57
	v_fmac_f32_e32 v106, v62, v62
	v_fmac_f32_e32 v107, v64, v64
	v_fmac_f32_e32 v108, v58, v58
	v_fmac_f32_e32 v109, v60, v60
	s_waitcnt vmcnt(28)
	v_mul_f32_e32 v112, v51, v51
	v_mul_f32_e32 v113, v53, v53
	v_fmac_f32_e32 v110, v54, v54
	v_fmac_f32_e32 v111, v56, v56
	v_add_f32_e32 v106, v106, v107
	v_add_f32_e32 v107, v108, v109
	v_fmac_f32_e32 v112, v50, v50
	v_fmac_f32_e32 v113, v52, v52
	v_add_f32_e32 v108, v110, v111
	v_add_f32_e32 v106, v106, v107
	v_add_f32_e32 v109, v112, v113
	v_add_f32_e32 v106, v106, v108
	v_add_f32_e32 v106, v106, v109
	s_waitcnt vmcnt(27)
	v_mul_f32_e32 v114, v47, v47
	v_mul_f32_e32 v115, v49, v49
	s_waitcnt vmcnt(26)
	v_mul_f32_e32 v116, v43, v43
	v_mul_f32_e32 v117, v45, v45
	v_fmac_f32_e32 v114, v46, v46
	v_fmac_f32_e32 v115, v48, v48
	s_waitcnt vmcnt(25)
	v_mul_f32_e32 v118, v39, v39
	v_mul_f32_e32 v119, v41, v41
	v_fmac_f32_e32 v116, v42, v42
	v_fmac_f32_e32 v117, v44, v44
	v_add_f32_e32 v107, v114, v115
	s_waitcnt vmcnt(24)
	v_mul_f32_e32 v120, v35, v35
	v_mul_f32_e32 v121, v37, v37
	v_fmac_f32_e32 v118, v38, v38
	v_fmac_f32_e32 v119, v40, v40
	v_add_f32_e32 v114, v116, v117
	v_add_f32_e32 v106, v106, v107
	v_fmac_f32_e32 v120, v34, v34
	v_fmac_f32_e32 v121, v36, v36
	s_waitcnt vmcnt(23)
	v_mul_f32_e32 v110, v31, v31
	v_mul_f32_e32 v111, v33, v33
	v_add_f32_e32 v115, v118, v119
	v_add_f32_e32 v106, v106, v114
	s_waitcnt vmcnt(22)
	v_mul_f32_e32 v112, v27, v27
	v_mul_f32_e32 v113, v29, v29
	v_add_f32_e32 v116, v120, v121
	v_fmac_f32_e32 v110, v30, v30
	v_fmac_f32_e32 v111, v32, v32
	v_add_f32_e32 v106, v106, v115
	s_waitcnt vmcnt(21)
	v_mul_f32_e32 v122, v23, v23
	v_mul_f32_e32 v123, v25, v25
	v_fmac_f32_e32 v112, v26, v26
	v_fmac_f32_e32 v113, v28, v28
	v_add_f32_e32 v108, v110, v111
	v_add_f32_e32 v106, v106, v116
	v_fmac_f32_e32 v122, v22, v22
	v_fmac_f32_e32 v123, v24, v24
	v_add_f32_e32 v110, v112, v113
	v_add_f32_e32 v106, v106, v108
	v_add_f32_e32 v106, v106, v110
	v_add_f32_e32 v107, v122, v123
	v_add_f32_e32 v106, v106, v107
	s_waitcnt vmcnt(20)
	v_mul_f32_e32 v107, v19, v19
	v_mul_f32_e32 v108, v21, v21
	v_fmac_f32_e32 v107, v18, v18
	v_fmac_f32_e32 v108, v20, v20
	v_add_f32_e32 v107, v107, v108
	s_nop 0
	v_add_f32_e32 v106, v106, v107
	s_waitcnt vmcnt(19)
	v_mul_f32_e32 v107, v15, v15
	v_mul_f32_e32 v108, v17, v17
	v_fmac_f32_e32 v107, v14, v14
	v_fmac_f32_e32 v108, v16, v16
	v_add_f32_e32 v107, v107, v108
	v_add_f32_e32 v106, v106, v107
	s_waitcnt vmcnt(18)
	v_mul_f32_e32 v107, v11, v11
	v_mul_f32_e32 v108, v13, v13
	v_fmac_f32_e32 v107, v10, v10
	v_fmac_f32_e32 v108, v12, v12
	v_add_f32_e32 v107, v107, v108
	v_add_f32_e32 v106, v106, v107
	s_waitcnt vmcnt(17)
	v_mul_f32_e32 v107, v7, v7
	v_mul_f32_e32 v108, v9, v9
	v_fmac_f32_e32 v107, v6, v6
	v_fmac_f32_e32 v108, v8, v8
	v_add_f32_e32 v107, v107, v108
	v_add_f32_e32 v106, v106, v107
	s_waitcnt vmcnt(16)
	v_mul_f32_e32 v107, v3, v3
	v_mul_f32_e32 v108, v5, v5
	v_fmac_f32_e32 v107, v2, v2
	v_fmac_f32_e32 v108, v4, v4
	v_add_f32_e32 v107, v107, v108
	v_add_f32_e32 v106, v106, v107
	ds_bpermute_b32 v107, v100, v106
	s_waitcnt lgkmcnt(0)
	v_add_f32_e32 v106, v106, v107
	ds_bpermute_b32 v107, v101, v106
	s_waitcnt lgkmcnt(0)
	v_add_f32_e32 v106, v106, v107
	ds_bpermute_b32 v107, v102, v106
	s_waitcnt lgkmcnt(0)
	v_add_f32_e32 v106, v106, v107
	ds_bpermute_b32 v107, v103, v106
	s_waitcnt lgkmcnt(0)
	v_add_f32_e32 v106, v106, v107
	ds_bpermute_b32 v107, v104, v106
	s_waitcnt lgkmcnt(0)
	v_add_f32_e32 v106, v106, v107
	ds_bpermute_b32 v107, v105, v106
	s_waitcnt lgkmcnt(0)
	v_add_f32_e32 v106, v106, v107
	v_fmamk_f32 v106, v106, 0x39800000, v1
	v_mul_f32_e32 v107, 0x4f800000, v106
	v_cmp_gt_f32_e32 vcc, s2, v106
	s_nop 1
	v_cndmask_b32_e32 v106, v106, v107, vcc
	v_sqrt_f32_e32 v107, v106
	s_nop 0
	v_add_u32_e32 v108, -1, v107
	v_fma_f32 v109, -v108, v107, v106
	v_cmp_ge_f32_e64 s[6:7], 0, v109
	v_add_u32_e32 v109, 1, v107
	s_nop 0
	v_cndmask_b32_e64 v108, v107, v108, s[6:7]
	v_fma_f32 v107, -v109, v107, v106
	v_cmp_lt_f32_e64 s[6:7], 0, v107
	s_nop 1
	v_cndmask_b32_e64 v107, v108, v109, s[6:7]
	v_mul_f32_e32 v108, 0x37800000, v107
	v_cndmask_b32_e32 v107, v107, v108, vcc
	v_cmp_class_f32_e32 vcc, v106, v66
	s_nop 1
	v_cndmask_b32_e32 v106, v107, v106, vcc
	v_div_scale_f32 v107, s[6:7], v106, v106, 1.0
	v_rcp_f32_e32 v108, v107
	s_nop 0
	v_fma_f32 v109, -v107, v108, 1.0
	v_fmac_f32_e32 v108, v109, v108
	v_div_scale_f32 v109, vcc, 1.0, v106, 1.0
	v_mul_f32_e32 v114, v109, v108
	v_fma_f32 v115, -v107, v114, v109
	v_fmac_f32_e32 v114, v115, v108
	v_fma_f32 v107, -v107, v114, v109
	v_div_fmas_f32 v107, v107, v108, v114
	v_div_fixup_f32 v109, v107, v106, 1.0
	v_mul_f32_e32 v62, v62, v109
	s_waitcnt vmcnt(15)
	v_mul_f32_e32 v108, v128, v62
	v_mul_f32_e32 v62, v63, v109
	v_mul_f32_e32 v107, v129, v62
	v_mul_f32_e32 v62, v64, v109
	v_mul_f32_e32 v106, v130, v62
	v_mul_f32_e32 v62, v65, v109
	v_mul_f32_e32 v64, v131, v62
	v_bfe_u32 v62, v108, 16, 1
	v_add3_u32 v62, v108, v62, s13
	v_bfe_u32 v63, v107, 16, 1
	v_lshrrev_b32_e32 v62, 16, v62
	v_add3_u32 v63, v107, v63, s13
	v_and_or_b32 v110, v63, s14, v62
	v_bfe_u32 v62, v106, 16, 1
	v_add3_u32 v62, v106, v62, s13
	v_bfe_u32 v63, v64, 16, 1
	v_lshl_add_u64 v[114:115], s[10:11], 0, v[96:97]
	v_lshrrev_b32_e32 v62, 16, v62
	v_add3_u32 v63, v64, v63, s13
	v_and_or_b32 v111, v63, s14, v62
	v_add_co_u32_e32 v62, vcc, s22, v114
	v_mul_f32_e32 v58, v58, v109
	s_nop 0
	v_addc_co_u32_e32 v63, vcc, 0, v115, vcc
	global_store_dwordx2 v[62:63], v[110:111], off offset:-4096
	s_nop 0
	v_mul_f32_e32 v59, v59, v109
	v_mul_f32_e32 v65, v60, v109
	v_mul_f32_e32 v116, v61, v109
	v_add_co_u32_e32 v114, vcc, s15, v114
	v_mul_f32_e32 v54, v54, v109
	s_nop 0
	v_addc_co_u32_e32 v115, vcc, 0, v115, vcc
	v_mul_f32_e32 v55, v55, v109
	v_mul_f32_e32 v50, v50, v109
	v_mul_f32_e32 v51, v51, v109
	v_mul_f32_e32 v46, v46, v109
	v_mul_f32_e32 v47, v47, v109
	v_mul_f32_e32 v42, v42, v109
	v_mul_f32_e32 v43, v43, v109
	v_mul_f32_e32 v38, v38, v109
	v_mul_f32_e32 v39, v39, v109
	v_mul_f32_e32 v34, v34, v109
	v_mul_f32_e32 v35, v35, v109
	v_mul_f32_e32 v30, v30, v109
	v_mul_f32_e32 v31, v31, v109
	v_mul_f32_e32 v26, v26, v109
	v_mul_f32_e32 v27, v27, v109
	v_mul_f32_e32 v22, v22, v109
	v_mul_f32_e32 v23, v23, v109
	v_mul_f32_e32 v18, v18, v109
	v_mul_f32_e32 v19, v19, v109
	v_mul_f32_e32 v14, v14, v109
	v_mul_f32_e32 v15, v15, v109
	v_mul_f32_e32 v10, v10, v109
	v_mul_f32_e32 v11, v11, v109
	v_mul_f32_e32 v6, v6, v109
	v_mul_f32_e32 v7, v7, v109
	v_mul_f32_e32 v2, v2, v109
	v_mul_f32_e32 v3, v3, v109
	v_mul_f32_e32 v4, v4, v109
	s_waitcnt vmcnt(15)
	v_mul_f32_e32 v61, v132, v58
	v_mul_f32_e32 v60, v133, v59
	v_mul_f32_e32 v59, v134, v65
	v_mul_f32_e32 v58, v135, v116
	v_bfe_u32 v65, v61, 16, 1
	v_bfe_u32 v111, v59, 16, 1
	v_bfe_u32 v110, v60, 16, 1
	v_bfe_u32 v112, v58, 16, 1
	v_add3_u32 v65, v61, v65, s13
	v_add3_u32 v111, v59, v111, s13
	v_add3_u32 v110, v60, v110, s13
	v_add3_u32 v112, v58, v112, s13
	v_lshrrev_b32_e32 v65, 16, v65
	v_lshrrev_b32_e32 v111, 16, v111
	v_and_or_b32 v110, v110, s14, v65
	v_and_or_b32 v111, v112, s14, v111
	global_store_dwordx2 v[114:115], v[110:111], off offset:512
	s_nop 0
	v_mul_f32_e32 v65, v56, v109
	v_mul_f32_e32 v116, v57, v109
	s_waitcnt vmcnt(15)
	v_mul_f32_e32 v57, v136, v54
	v_mul_f32_e32 v56, v137, v55
	v_mul_f32_e32 v55, v138, v65
	v_mul_f32_e32 v54, v139, v116
	v_bfe_u32 v65, v57, 16, 1
	v_bfe_u32 v111, v55, 16, 1
	v_bfe_u32 v110, v56, 16, 1
	v_bfe_u32 v112, v54, 16, 1
	v_add3_u32 v65, v57, v65, s13
	v_add3_u32 v111, v55, v111, s13
	v_add3_u32 v110, v56, v110, s13
	v_add3_u32 v112, v54, v112, s13
	v_lshrrev_b32_e32 v65, 16, v65
	v_lshrrev_b32_e32 v111, 16, v111
	v_and_or_b32 v110, v110, s14, v65
	v_and_or_b32 v111, v112, s14, v111
	global_store_dwordx2 v[114:115], v[110:111], off offset:1024
	s_nop 0
	v_mul_f32_e32 v65, v52, v109
	v_mul_f32_e32 v116, v53, v109
	s_waitcnt vmcnt(15)
	v_mul_f32_e32 v53, v50, v140
	v_mul_f32_e32 v52, v51, v141
	v_mul_f32_e32 v51, v65, v142
	v_mul_f32_e32 v50, v116, v143
	v_bfe_u32 v65, v53, 16, 1
	v_bfe_u32 v111, v51, 16, 1
	v_bfe_u32 v110, v52, 16, 1
	v_bfe_u32 v112, v50, 16, 1
	v_add3_u32 v65, v53, v65, s13
	v_add3_u32 v111, v51, v111, s13
	v_add3_u32 v110, v52, v110, s13
	v_add3_u32 v112, v50, v112, s13
	v_lshrrev_b32_e32 v65, 16, v65
	v_lshrrev_b32_e32 v111, 16, v111
	v_and_or_b32 v110, v110, s14, v65
	v_and_or_b32 v111, v112, s14, v111
	global_store_dwordx2 v[114:115], v[110:111], off offset:1536
	s_nop 0
	v_mul_f32_e32 v65, v48, v109
	v_mul_f32_e32 v116, v49, v109
	s_waitcnt vmcnt(15)
	v_mul_f32_e32 v49, v46, v144
	v_mul_f32_e32 v48, v47, v145
	v_mul_f32_e32 v47, v65, v146
	v_mul_f32_e32 v46, v116, v147
	v_bfe_u32 v65, v49, 16, 1
	v_bfe_u32 v111, v47, 16, 1
	v_bfe_u32 v110, v48, 16, 1
	v_bfe_u32 v112, v46, 16, 1
	v_add3_u32 v65, v49, v65, s13
	v_add3_u32 v111, v47, v111, s13
	v_add3_u32 v110, v48, v110, s13
	v_add3_u32 v112, v46, v112, s13
	v_lshrrev_b32_e32 v65, 16, v65
	v_lshrrev_b32_e32 v111, 16, v111
	v_and_or_b32 v110, v110, s14, v65
	v_and_or_b32 v111, v112, s14, v111
	global_store_dwordx2 v[114:115], v[110:111], off offset:2048
	s_nop 0
	v_mul_f32_e32 v65, v44, v109
	v_mul_f32_e32 v116, v45, v109
	s_waitcnt vmcnt(15)
	v_mul_f32_e32 v45, v42, v148
	v_mul_f32_e32 v44, v43, v149
	v_mul_f32_e32 v43, v65, v150
	v_mul_f32_e32 v42, v116, v151
	v_bfe_u32 v65, v45, 16, 1
	v_bfe_u32 v111, v43, 16, 1
	v_bfe_u32 v110, v44, 16, 1
	v_bfe_u32 v112, v42, 16, 1
	v_add3_u32 v65, v45, v65, s13
	v_add3_u32 v111, v43, v111, s13
	v_add3_u32 v110, v44, v110, s13
	v_add3_u32 v112, v42, v112, s13
	v_lshrrev_b32_e32 v65, 16, v65
	v_lshrrev_b32_e32 v111, 16, v111
	v_and_or_b32 v110, v110, s14, v65
	v_and_or_b32 v111, v112, s14, v111
	global_store_dwordx2 v[114:115], v[110:111], off offset:2560
	s_nop 0
	v_mul_f32_e32 v65, v40, v109
	v_mul_f32_e32 v116, v41, v109
	s_waitcnt vmcnt(15)
	v_mul_f32_e32 v41, v38, v152
	v_mul_f32_e32 v40, v39, v153
	v_mul_f32_e32 v39, v65, v154
	v_mul_f32_e32 v38, v116, v155
	v_bfe_u32 v65, v41, 16, 1
	v_bfe_u32 v111, v39, 16, 1
	v_bfe_u32 v110, v40, 16, 1
	v_bfe_u32 v112, v38, 16, 1
	v_add3_u32 v65, v41, v65, s13
	v_add3_u32 v111, v39, v111, s13
	v_add3_u32 v110, v40, v110, s13
	v_add3_u32 v112, v38, v112, s13
	v_lshrrev_b32_e32 v65, 16, v65
	v_lshrrev_b32_e32 v111, 16, v111
	v_and_or_b32 v110, v110, s14, v65
	v_and_or_b32 v111, v112, s14, v111
	global_store_dwordx2 v[114:115], v[110:111], off offset:3072
	s_nop 0
	v_mul_f32_e32 v65, v36, v109
	v_mul_f32_e32 v116, v37, v109
	s_waitcnt vmcnt(15)
	v_mul_f32_e32 v37, v34, v156
	v_mul_f32_e32 v36, v35, v157
	v_mul_f32_e32 v35, v65, v158
	v_mul_f32_e32 v34, v116, v159
	v_bfe_u32 v65, v37, 16, 1
	v_bfe_u32 v111, v35, 16, 1
	v_bfe_u32 v110, v36, 16, 1
	v_bfe_u32 v112, v34, 16, 1
	v_add3_u32 v65, v37, v65, s13
	v_add3_u32 v111, v35, v111, s13
	v_add3_u32 v110, v36, v110, s13
	v_add3_u32 v112, v34, v112, s13
	v_lshrrev_b32_e32 v65, 16, v65
	v_lshrrev_b32_e32 v111, 16, v111
	v_and_or_b32 v110, v110, s14, v65
	v_and_or_b32 v111, v112, s14, v111
	global_store_dwordx2 v[114:115], v[110:111], off offset:3584
	s_nop 0
	v_mul_f32_e32 v65, v32, v109
	v_mul_f32_e32 v114, v33, v109
	s_waitcnt vmcnt(15)
	v_mul_f32_e32 v33, v30, v160
	v_mul_f32_e32 v32, v31, v161
	v_mul_f32_e32 v31, v65, v162
	v_mul_f32_e32 v30, v114, v163
	v_bfe_u32 v65, v33, 16, 1
	v_bfe_u32 v111, v31, 16, 1
	v_bfe_u32 v110, v32, 16, 1
	v_bfe_u32 v112, v30, 16, 1
	v_add3_u32 v65, v33, v65, s13
	v_add3_u32 v111, v31, v111, s13
	v_add3_u32 v110, v32, v110, s13
	v_add3_u32 v112, v30, v112, s13
	v_lshrrev_b32_e32 v65, 16, v65
	v_lshrrev_b32_e32 v111, 16, v111
	v_and_or_b32 v110, v110, s14, v65
	v_and_or_b32 v111, v112, s14, v111
	global_store_dwordx2 v[62:63], v[110:111], off
	s_nop 0
	v_mul_f32_e32 v65, v28, v109
	v_mul_f32_e32 v114, v29, v109
	s_waitcnt vmcnt(15)
	v_mul_f32_e32 v29, v26, v164
	v_mul_f32_e32 v28, v27, v165
	v_mul_f32_e32 v27, v65, v166
	v_mul_f32_e32 v26, v114, v167
	v_bfe_u32 v65, v29, 16, 1
	v_bfe_u32 v111, v27, 16, 1
	v_bfe_u32 v110, v28, 16, 1
	v_bfe_u32 v112, v26, 16, 1
	v_add3_u32 v65, v29, v65, s13
	v_add3_u32 v111, v27, v111, s13
	v_add3_u32 v110, v28, v110, s13
	v_add3_u32 v112, v26, v112, s13
	v_lshrrev_b32_e32 v65, 16, v65
	v_lshrrev_b32_e32 v111, 16, v111
	v_and_or_b32 v110, v110, s14, v65
	v_and_or_b32 v111, v112, s14, v111
	global_store_dwordx2 v[62:63], v[110:111], off offset:512
	s_nop 0
	v_mul_f32_e32 v65, v24, v109
	v_mul_f32_e32 v114, v25, v109
	s_waitcnt vmcnt(15)
	v_mul_f32_e32 v25, v22, v168
	v_mul_f32_e32 v24, v23, v169
	v_mul_f32_e32 v23, v65, v170
	v_mul_f32_e32 v22, v114, v171
	v_bfe_u32 v65, v25, 16, 1
	v_bfe_u32 v111, v23, 16, 1
	v_bfe_u32 v110, v24, 16, 1
	v_bfe_u32 v112, v22, 16, 1
	v_add3_u32 v65, v25, v65, s13
	v_add3_u32 v111, v23, v111, s13
	v_add3_u32 v110, v24, v110, s13
	v_add3_u32 v112, v22, v112, s13
	v_lshrrev_b32_e32 v65, 16, v65
	v_lshrrev_b32_e32 v111, 16, v111
	v_and_or_b32 v110, v110, s14, v65
	v_and_or_b32 v111, v112, s14, v111
	global_store_dwordx2 v[62:63], v[110:111], off offset:1024
	s_nop 0
	v_mul_f32_e32 v65, v20, v109
	v_mul_f32_e32 v114, v21, v109
	s_waitcnt vmcnt(15)
	v_mul_f32_e32 v21, v18, v172
	v_mul_f32_e32 v20, v19, v173
	v_mul_f32_e32 v19, v65, v174
	v_mul_f32_e32 v18, v114, v175
	v_bfe_u32 v65, v21, 16, 1
	v_bfe_u32 v111, v19, 16, 1
	v_bfe_u32 v110, v20, 16, 1
	v_bfe_u32 v112, v18, 16, 1
	v_add3_u32 v65, v21, v65, s13
	v_add3_u32 v111, v19, v111, s13
	v_add3_u32 v110, v20, v110, s13
	v_add3_u32 v112, v18, v112, s13
	v_lshrrev_b32_e32 v65, 16, v65
	v_lshrrev_b32_e32 v111, 16, v111
	v_and_or_b32 v110, v110, s14, v65
	v_and_or_b32 v111, v112, s14, v111
	global_store_dwordx2 v[62:63], v[110:111], off offset:1536
	s_nop 0
	v_mul_f32_e32 v65, v16, v109
	v_mul_f32_e32 v114, v17, v109
	s_waitcnt vmcnt(15)
	v_mul_f32_e32 v17, v14, v176
	v_mul_f32_e32 v16, v15, v177
	v_mul_f32_e32 v15, v65, v178
	v_mul_f32_e32 v14, v114, v179
	v_bfe_u32 v65, v17, 16, 1
	v_bfe_u32 v111, v15, 16, 1
	v_bfe_u32 v110, v16, 16, 1
	v_bfe_u32 v112, v14, 16, 1
	v_add3_u32 v65, v17, v65, s13
	v_add3_u32 v111, v15, v111, s13
	v_add3_u32 v110, v16, v110, s13
	v_add3_u32 v112, v14, v112, s13
	v_lshrrev_b32_e32 v65, 16, v65
	v_lshrrev_b32_e32 v111, 16, v111
	v_and_or_b32 v110, v110, s14, v65
	v_and_or_b32 v111, v112, s14, v111
	global_store_dwordx2 v[62:63], v[110:111], off offset:2048
	s_nop 0
	v_mul_f32_e32 v65, v12, v109
	v_mul_f32_e32 v114, v13, v109
	s_waitcnt vmcnt(15)
	v_mul_f32_e32 v13, v10, v180
	v_mul_f32_e32 v12, v11, v181
	v_mul_f32_e32 v11, v65, v182
	v_mul_f32_e32 v10, v114, v183
	v_bfe_u32 v65, v13, 16, 1
	v_bfe_u32 v111, v11, 16, 1
	v_bfe_u32 v110, v12, 16, 1
	v_bfe_u32 v112, v10, 16, 1
	v_add3_u32 v65, v13, v65, s13
	v_add3_u32 v111, v11, v111, s13
	v_add3_u32 v110, v12, v110, s13
	v_add3_u32 v112, v10, v112, s13
	v_lshrrev_b32_e32 v65, 16, v65
	v_lshrrev_b32_e32 v111, 16, v111
	v_and_or_b32 v110, v110, s14, v65
	v_and_or_b32 v111, v112, s14, v111
	global_store_dwordx2 v[62:63], v[110:111], off offset:2560
	s_nop 0
	v_mul_f32_e32 v65, v8, v109
	v_mul_f32_e32 v114, v9, v109
	s_waitcnt vmcnt(15)
	v_mul_f32_e32 v9, v6, v184
	v_mul_f32_e32 v8, v7, v185
	v_mul_f32_e32 v7, v65, v186
	v_mul_f32_e32 v6, v114, v187
	v_bfe_u32 v65, v9, 16, 1
	v_bfe_u32 v111, v7, 16, 1
	v_bfe_u32 v110, v8, 16, 1
	v_bfe_u32 v112, v6, 16, 1
	v_add3_u32 v65, v9, v65, s13
	v_add3_u32 v111, v7, v111, s13
	v_add3_u32 v110, v8, v110, s13
	v_add3_u32 v112, v6, v112, s13
	v_lshrrev_b32_e32 v65, 16, v65
	v_lshrrev_b32_e32 v111, 16, v111
	v_and_or_b32 v110, v110, s14, v65
	v_and_or_b32 v111, v112, s14, v111
	global_store_dwordx2 v[62:63], v[110:111], off offset:3072
	s_nop 0
	v_mul_f32_e32 v114, v5, v109
	v_max_f32_e64 v5, |v108|, |v107|
	v_max_f32_e64 v65, |v106|, |v64|
	v_max3_f32 v5, v5, 0, v65
	v_max_f32_e64 v65, |v61|, |v60|
	v_max_f32_e64 v109, |v59|, |v58|
	v_max3_f32 v5, v5, v65, v109
	v_max_f32_e64 v65, |v57|, |v56|
	v_max_f32_e64 v109, |v55|, |v54|
	v_max3_f32 v5, v5, v65, v109
	v_max_f32_e64 v65, |v53|, |v52|
	v_max_f32_e64 v109, |v51|, |v50|
	v_max3_f32 v5, v5, v65, v109
	v_max_f32_e64 v65, |v49|, |v48|
	v_max_f32_e64 v109, |v47|, |v46|
	v_max3_f32 v5, v5, v65, v109
	v_max_f32_e64 v65, |v45|, |v44|
	v_max_f32_e64 v109, |v43|, |v42|
	v_max3_f32 v5, v5, v65, v109
	v_max_f32_e64 v65, |v41|, |v40|
	v_max_f32_e64 v109, |v39|, |v38|
	v_max3_f32 v5, v5, v65, v109
	v_max_f32_e64 v65, |v37|, |v36|
	v_max_f32_e64 v109, |v35|, |v34|
	v_max3_f32 v5, v5, v65, v109
	v_max_f32_e64 v65, |v33|, |v32|
	v_max_f32_e64 v109, |v31|, |v30|
	v_max3_f32 v5, v5, v65, v109
	v_max_f32_e64 v65, |v29|, |v28|
	v_max_f32_e64 v109, |v27|, |v26|
	v_max3_f32 v5, v5, v65, v109
	v_max_f32_e64 v65, |v25|, |v24|
	v_max_f32_e64 v109, |v23|, |v22|
	v_max3_f32 v5, v5, v65, v109
	v_max_f32_e64 v65, |v21|, |v20|
	v_max_f32_e64 v109, |v19|, |v18|
	v_max3_f32 v5, v5, v65, v109
	v_max_f32_e64 v65, |v17|, |v16|
	v_max_f32_e64 v109, |v15|, |v14|
	v_max3_f32 v5, v5, v65, v109
	v_max_f32_e64 v65, |v13|, |v12|
	v_max_f32_e64 v109, |v11|, |v10|
	v_max3_f32 v5, v5, v65, v109
	v_max_f32_e64 v65, |v9|, |v8|
	v_max_f32_e64 v109, |v7|, |v6|
	v_max3_f32 v115, v5, v65, v109
	s_waitcnt vmcnt(15)
	v_mul_f32_e32 v109, v2, v188
	v_mul_f32_e32 v65, v3, v189
	v_mul_f32_e32 v5, v4, v190
	v_mul_f32_e32 v4, v114, v191
	v_max_f32_e64 v2, |v109|, |v65|
	v_max_f32_e64 v3, |v5|, |v4|
	v_max3_f32 v2, v115, v2, v3
	ds_bpermute_b32 v3, v100, v2
	v_bfe_u32 v110, v109, 16, 1
	v_add3_u32 v110, v109, v110, s13
	v_bfe_u32 v111, v65, 16, 1
	v_lshrrev_b32_e32 v110, 16, v110
	s_waitcnt lgkmcnt(0)
	v_max_f32_e32 v3, v3, v3
	v_max_f32_e32 v2, v2, v3
	ds_bpermute_b32 v3, v101, v2
	v_add3_u32 v111, v65, v111, s13
	s_waitcnt lgkmcnt(0)
	v_max_f32_e32 v3, v3, v3
	v_max_f32_e32 v2, v2, v3
	ds_bpermute_b32 v3, v102, v2
	s_waitcnt lgkmcnt(0)
	v_max_f32_e32 v3, v3, v3
	v_max_f32_e32 v2, v2, v3
	ds_bpermute_b32 v3, v103, v2
	s_waitcnt lgkmcnt(0)
	v_max_f32_e32 v3, v3, v3
	v_max_f32_e32 v3, v2, v3
	ds_bpermute_b32 v112, v104, v3
	v_and_or_b32 v2, v111, s14, v110
	v_bfe_u32 v110, v5, 16, 1
	v_add3_u32 v110, v5, v110, s13
	v_lshrrev_b32_e32 v110, 16, v110
	s_waitcnt lgkmcnt(0)
	v_max_f32_e32 v111, v112, v112
	v_max_f32_e32 v111, v3, v111
	ds_bpermute_b32 v112, v105, v111
	v_bfe_u32 v3, v4, 16, 1
	v_add3_u32 v3, v4, v3, s13
	v_and_or_b32 v3, v3, s14, v110
	global_store_dwordx2 v[62:63], v[2:3], off offset:3584
	s_waitcnt lgkmcnt(0)
	v_max3_f32 v2, v111, v112, s23
	s_and_saveexec_b64 s[6:7], s[4:5]
	s_cbranch_execz .LBB0_690
	s_add_u32 s28, s10, s0
	v_mul_f32_e32 v3, 0x3c010204, v2
	s_addc_u32 s29, s11, s1
	global_store_dword v67, v3, s[28:29]
	s_branch .LBB0_690

.LBB0_2771:
	s_andn2_b64 vcc, exec, s[12:13]
	s_cbranch_vccnz .LBB0_2782
	s_lshl_b64 s[16:17], s[74:75], 2
	s_add_u32 s16, s39, s16
	s_addc_u32 s17, s40, s17
	s_load_dword s98, s[16:17], 0x0
	v_mov_b32_e32 v20, 0
	s_mov_b32 s15, 0
	v_mov_b32_e32 v122, 1.0
	v_mov_b32_e32 v118, v115
	v_mov_b32_e32 v119, v114
	s_mov_b32 s18, s45
	v_mov_b32_e32 v120, v113
	v_mov_b32_e32 v121, v112
	v_mov_b32_e32 v21, v20
	v_mov_b32_e32 v22, v20
	v_mov_b32_e32 v23, v20
	v_mov_b32_e32 v24, v20
	v_mov_b32_e32 v25, v20
	v_mov_b32_e32 v26, v20
	v_mov_b32_e32 v27, v20
	v_mov_b32_e32 v28, v20
	v_mov_b32_e32 v29, v20
	v_mov_b32_e32 v30, v20
	v_mov_b32_e32 v31, v20
	v_mov_b32_e32 v32, v20
	v_mov_b32_e32 v33, v20
	v_mov_b32_e32 v34, v20
	v_mov_b32_e32 v35, v20
	v_mov_b32_e32 v4, v20
	v_mov_b32_e32 v5, v20
	v_mov_b32_e32 v6, v20
	v_mov_b32_e32 v7, v20
	v_mov_b32_e32 v8, v20
	v_mov_b32_e32 v9, v20
	v_mov_b32_e32 v10, v20
	v_mov_b32_e32 v11, v20
	v_mov_b32_e32 v12, v20
	v_mov_b32_e32 v13, v20
	v_mov_b32_e32 v14, v20
	v_mov_b32_e32 v15, v20
	v_mov_b32_e32 v16, v20
	v_mov_b32_e32 v17, v20
	v_mov_b32_e32 v18, v20
	s_waitcnt lgkmcnt(0)
	v_mov_b32_e32 v19, s98
	v_mul_f32_e32 v123, 0x3fb8aa3b, v19
	v_mov_b32_e32 v19, v20
